# v24 plus ffn_up epilogue: the 3-tap conv for (gate, up) done with packed f32 ops on (gate,up) register pairs, 8 fewer VALU per two rows
# baseline (speedup 1.0000x reference)
.LBB0_2107:
	s_or_b64 exec, exec, s[4:5]
	s_xor_b64 s[4:5], s[14:15], -1
	s_lshl_b32 s14, s17, 6
	s_or_b32 s14, s14, s16
	v_or_b32_e32 v130, s14, v1
	v_mov_b32_e32 v131, v0
	v_lshlrev_b64 v[136:137], 2, v[130:131]
	v_lshl_add_u64 v[140:141], s[6:7], 0, v[136:137]
	v_add_co_u32_e32 v132, vcc, 0x8000, v140
	v_or_b32_e32 v138, 0x1000, v130
	s_nop 0
	v_addc_co_u32_e32 v133, vcc, 0, v141, vcc
	v_mov_b32_e32 v139, v0
	v_add_co_u32_e32 v134, vcc, 0x10000, v140
	v_lshlrev_b64 v[138:139], 2, v[138:139]
	s_nop 0
	v_addc_co_u32_e32 v135, vcc, 0, v141, vcc
	v_lshl_add_u64 v[142:143], s[6:7], 0, v[138:139]
	s_waitcnt lgkmcnt(0)
	s_barrier
	global_load_dword v131, v[140:141], off
	v_lshl_add_u64 v[136:137], s[8:9], 0, v[136:137]
	global_load_dword v133, v[132:133], off
	v_lshl_add_u64 v[138:139], s[8:9], 0, v[138:139]
	global_load_dword v135, v[134:135], off
	s_lshl_b32 s84, s14, 1
	global_load_dword v132, v[142:143], off
	v_add_co_u32_e32 v142, vcc, s67, v140
	global_load_dword v137, v[136:137], off
	s_nop 0
	v_addc_co_u32_e32 v143, vcc, 0, v141, vcc
	v_add_co_u32_e32 v140, vcc, 0x14000, v140
	global_load_dword v130, v[142:143], off
	s_nop 0
	v_addc_co_u32_e32 v141, vcc, 0, v141, vcc
	global_load_dword v134, v[140:141], off
	global_load_dword v136, v[138:139], off
	v_lshl_add_u64 v[138:139], v[178:179], 0, s[84:85]
	s_movk_i32 s17, 0xfbf8
	v_mov_b32_e32 v142, v206
	s_waitcnt vmcnt(0)
	s_movk_i32 s18, 0x7fff
	v_mov_b32_e32 v180, v131
	v_mov_b32_e32 v181, v132
	v_mov_b32_e32 v182, v133
	v_mov_b32_e32 v183, v130
	v_mov_b32_e32 v184, v135
	v_mov_b32_e32 v185, v134
	v_mov_b32_e32 v186, v137
	v_mov_b32_e32 v187, v136
.Lffn_row2:
	v_add_u32_e32 v152, s17, v207
	ds_read2st64_b32 v[154:155], v152 offset1:1
	ds_read2_b32 v[156:157], v152 offset0:129 offset1:193
	v_add_u32_e32 v153, 8, v152
	ds_read2st64_b32 v[158:159], v153 offset0:4 offset1:5
	v_add_u32_e32 v153, 0x60c, v152
	ds_read2st64_b32 v[160:161], v153 offset1:1
	v_add_u32_e32 v162, s31, v142
	v_add_u32_e32 v163, 1, v162
	v_cmp_lt_i32_e64 s[20:21], 1, v142
	v_cmp_gt_i32_e32 vcc, s34, v162
	v_ashrrev_i32_e32 v165, 31, v162
	v_mov_b32_e32 v164, v162
	s_and_b64 s[20:21], s[20:21], vcc
	v_cmp_lt_i32_e64 s[22:23], 0, v142
	v_cmp_gt_i32_e32 vcc, s34, v163
	v_lshlrev_b64 v[164:165], 13, v[164:165]
	v_lshl_add_u64 v[164:165], v[138:139], 0, v[164:165]
	s_and_b64 s[22:23], s[22:23], vcc
	v_add_co_u32_e32 v166, vcc, 0x2000, v164
	s_nop 1
	v_addc_co_u32_e32 v167, vcc, 0, v165, vcc
	s_waitcnt lgkmcnt(0)
	v_pk_mul_f32 v[168:169], v[182:183], v[156:157]
	v_pk_mul_f32 v[170:171], v[182:183], v[158:159]
	v_pk_fma_f32 v[168:169], v[180:181], v[154:155], v[168:169]
	v_pk_fma_f32 v[170:171], v[180:181], v[156:157], v[170:171]
	v_pk_fma_f32 v[168:169], v[184:185], v[158:159], v[168:169]
	v_pk_fma_f32 v[170:171], v[184:185], v[160:161], v[170:171]
	v_pk_add_f32 v[168:169], v[186:187], v[168:169]
	v_pk_add_f32 v[170:171], v[186:187], v[170:171]
	s_nop 0
	v_mul_f32_e32 v172, 0xbfb8aa3b, v168
	v_mul_f32_e32 v173, 0xbfb8aa3b, v170
	v_exp_f32_e32 v172, v172
	v_exp_f32_e32 v173, v173
	s_nop 0
	v_add_f32_e32 v172, 1.0, v172
	v_add_f32_e32 v173, 1.0, v173
	v_rcp_f32_e32 v172, v172
	v_rcp_f32_e32 v173, v173
	s_nop 0
	v_mul_f32_e32 v172, v168, v172
	v_mul_f32_e32 v173, v170, v173
	v_mul_f32_e32 v172, v169, v172
	v_mul_f32_e32 v173, v171, v173
	v_bfe_u32 v174, v172, 16, 1
	v_bfe_u32 v175, v173, 16, 1
	v_add3_u32 v172, v172, v174, s18
	v_add3_u32 v173, v173, v175, s18
	s_mov_b64 s[14:15], exec
	s_and_b64 exec, s[14:15], s[20:21]
	global_store_short_d16_hi v[164:165], v172, off
	s_and_b64 exec, s[14:15], s[22:23]
	global_store_short_d16_hi v[166:167], v173, off
	s_mov_b64 exec, s[14:15]
	s_addk_i32 s17, 0x408
	v_add_u32_e32 v142, 2, v142
	s_cmpk_eq_i32 s17, 0x3c78
	s_cbranch_scc0 .Lffn_row2
	s_branch .LBB0_2104
